# attention preamble: batch the 160 key-scalar loads, drop full wait before first K/V loads, counted wait
# speedup vs baseline: 1.0386x; 1.0012x over previous
; __device__ __forceinline__ float part8(const float* p) { const f32x4 a = *(const f32x4*)p, b = *(const f32x4*)(p + 4); return ((a[0] + a[1]) + (a[2] + a[3])) + ((b[0] + b[1]) + (b[2] + b[3])); }
; __device__ __forceinline__ void attn_wave_unit(LAS unsigned char* wl, const bf16* __restrict__ Q, const bf16* __restrict__ Kb, const bf16* __restrict__ V, const float* ssq_x, const float* ssq_qk, ...
;     ...
;     for (int i = lane; i < 160; i += 64) {
;         int ka = a0 - 64 + i; ka = ka < 0 ? 0 : (ka > L - 1 ? L - 1 : ka); const int pos = r + d * ka;
;         const float rs = __builtin_amdgcn_rsqf(pg8::part8(ssq_x + (size_t)pos * 8) * (1.0f / 2048.0f) + EPSF);
;         const float sk = ssq_qk[(size_t)pos * 16 + 8 + h];
;         ckl[i] = rs * __builtin_amdgcn_rsqf(rs * rs * sk * (1.0f / 128.0f) + EPSF);
;     }
.LBB0_518:
	s_mov_b64 s[86:87], exec
	v_add_u32_e32 v2, s94, v233
	v_add_u32_e32 v3, 64, v2
	v_add_u32_e32 v4, 0x80, v2
	v_min_i32_e32 v5, s41, v2
	v_min_i32_e32 v6, s41, v3
	v_min_i32_e32 v7, s41, v4
	v_cmp_lt_i32_e32 vcc, -1, v2
	s_nop 1
	v_cndmask_b32_e32 v2, 0, v5, vcc
	v_cmp_lt_i32_e32 vcc, -1, v3
	s_nop 1
	v_cndmask_b32_e32 v3, 0, v6, vcc
	v_cmp_lt_i32_e32 vcc, -1, v4
	s_nop 1
	v_cndmask_b32_e32 v4, 0, v7, vcc
	v_mul_lo_u32 v2, v2, s92
	v_mul_lo_u32 v3, v3, s92
	v_mul_lo_u32 v4, v4, s92
	v_add_u32_e32 v12, s91, v2
	v_add_u32_e32 v13, s91, v3
	v_add_u32_e32 v14, s91, v4
	v_lshlrev_b32_e32 v8, 5, v12
	v_lshlrev_b32_e32 v9, 5, v13
	v_lshlrev_b32_e32 v10, 5, v14
	v_lshlrev_b32_e32 v43, 6, v12
	v_lshlrev_b32_e32 v44, 6, v13
	v_lshlrev_b32_e32 v45, 6, v14
	global_load_dwordx4 v[16:19], v8, s[14:15]
	global_load_dwordx4 v[20:23], v8, s[14:15] offset:16
	global_load_dwordx4 v[24:27], v9, s[14:15]
	global_load_dwordx4 v[28:31], v9, s[14:15] offset:16
	global_load_dwordx4 v[32:35], v10, s[14:15]
	global_load_dwordx4 v[36:39], v10, s[14:15] offset:16
	global_load_dword v40, v43, s[28:29] offset:32
	global_load_dword v41, v44, s[28:29] offset:32
	global_load_dword v42, v45, s[28:29] offset:32
	s_waitcnt vmcnt(0)
	v_add_f32_e32 v16, v16, v17
	v_add_f32_e32 v18, v18, v19
	v_add_f32_e32 v20, v20, v21
	v_add_f32_e32 v22, v22, v23
	v_add_f32_e32 v24, v24, v25
	v_add_f32_e32 v26, v26, v27
	v_add_f32_e32 v28, v28, v29
	v_add_f32_e32 v30, v30, v31
	v_add_f32_e32 v32, v32, v33
	v_add_f32_e32 v34, v34, v35
	v_add_f32_e32 v36, v36, v37
	v_add_f32_e32 v38, v38, v39
	v_add_f32_e32 v16, v16, v18
	v_add_f32_e32 v20, v20, v22
	v_add_f32_e32 v24, v24, v26
	v_add_f32_e32 v28, v28, v30
	v_add_f32_e32 v32, v32, v34
	v_add_f32_e32 v36, v36, v38
	v_add_f32_e32 v16, v16, v20
	v_add_f32_e32 v24, v24, v28
	v_add_f32_e32 v32, v32, v36
	v_fmamk_f32 v16, v16, 0x3a000000, v220
	v_fmamk_f32 v24, v24, 0x3a000000, v220
	v_fmamk_f32 v32, v32, 0x3a000000, v220
	v_rsq_f32_e32 v20, v16
	v_rsq_f32_e32 v28, v24
	v_rsq_f32_e32 v36, v32
	v_mul_f32_e32 v16, v20, v20
	v_mul_f32_e32 v24, v28, v28
	v_mul_f32_e32 v32, v36, v36
	v_mul_f32_e32 v16, v40, v16
	v_mul_f32_e32 v24, v41, v24
	v_mul_f32_e32 v32, v42, v32
	v_fmamk_f32 v16, v16, 0x3c000000, v220
	v_fmamk_f32 v24, v24, 0x3c000000, v220
	v_fmamk_f32 v32, v32, 0x3c000000, v220
	v_rsq_f32_e32 v16, v16
	v_rsq_f32_e32 v24, v24
	v_rsq_f32_e32 v32, v32
	v_mul_f32_e32 v16, v20, v16
	v_mul_f32_e32 v24, v28, v24
	v_mul_f32_e32 v32, v36, v32
	ds_write_b32 v232, v16
	ds_write_b32 v232, v24 offset:256
	s_mov_b32 vcc_lo, -1
	s_mov_b32 vcc_hi, 0
	s_and_b64 exec, s[86:87], vcc
	ds_write_b32 v232, v32 offset:512
	s_mov_b64 exec, s[86:87]
	s_or_b64 exec, exec, s[86:87]
	v_mov_b32_e32 v240, s41
	v_mov_b32_e32 v0, s40
; __device__ __forceinline__ float part8(const float* p) { const f32x4 a = *(const f32x4*)p, b = *(const f32x4*)(p + 4); return ((a[0] + a[1]) + (a[2] + a[3])) + ((b[0] + b[1]) + (b[2] + b[3])); }
; #define ATT_LOAD_KV(t_) do { _Pragma("unroll") for (int i = 0; i < 8; ++i) { int vi = a0 - 64 + 32 * (t_) + 4 * i + (lane >> 4); vi = vi < 0 ? 0 : (vi > L - 1 ? L - 1 : vi); \
;         const size_t go = (size_t)(r + d * vi) * 1024 + h * 128 + (lane & 15) * 8; kr[i] = *(const u32x4*)(Kb + go); vr[i] = *(const u32x4*)(V + go); } } while (0)
; __device__ __forceinline__ void attn_wave_unit(LAS unsigned char* wl, const bf16* __restrict__ Q, const bf16* __restrict__ Kb, const bf16* __restrict__ V, const float* ssq_x, const float* ssq_qk, ...
;     ...
;     const int aq = (a0 + qi) > L - 1 ? L - 1 : (a0 + qi); const int qpos = r + d * aq;
;     float cq;
;     { const float rs = __builtin_amdgcn_rsqf(pg8::part8(ssq_x + (size_t)qpos * 8) * (1.0f / 2048.0f) + EPSF); const float sq = ssq_qk[(size_t)qpos * 16 + h];
;       cq = rs * __builtin_amdgcn_rsqf(rs * rs * sq * (1.0f / 128.0f) + EPSF) * (0.08838834764831845f * 1.4426950408889634f); }
;     bf16x8 qf[8];
;     { const bf16* qrow = Q + (size_t)qpos * 1024 + h * 128 + 8 * hh;
; #pragma unroll
;       for (int ks = 0; ks < 8; ++ks) qf[ks] = *(const bf16x8*)(qrow + 16 * ks); }
;     f32x16 o[4];
; #pragma unroll
;     for (int db = 0; db < 4; ++db)
; #pragma unroll
;         for (int e = 0; e < 16; ++e) o[db][e] = 0.f;
;     float m_run = -1e30f, l_run = 0.f;
;     asm volatile("s_waitcnt lgkmcnt(0)" ::: "memory");
;     const int qa = a0 + qi;
;     const int trbase = (4 * hh + ((lane & 15) >> 2)) * VPITCH + (16 * ((lane >> 4) & 1) + 4 * (lane & 3)) * 2;
;     u32x4 kr[8], vr[8];
;     ...
;     ATT_LOAD_KV(0);
.LBB0_520:
	s_or_b64 exec, exec, s[84:85]
	v_add_u32_e32 v239, s94, v227
	v_min_i32_e32 v1, v239, v240
	v_mul_lo_u32 v1, v1, s92
	v_add_u32_e32 v216, s91, v1
	v_ashrrev_i32_e32 v217, 31, v216
	v_lshlrev_b64 v[214:215], 5, v[216:217]
	v_lshl_add_u64 v[6:7], s[14:15], 0, v[214:215]
	flat_load_dwordx4 v[2:5], v[6:7]
	s_nop 0
	flat_load_dwordx4 v[6:9], v[6:7] offset:16
	v_add_u32_e32 v16, v0, v228
	v_min_u32_e32 v0, v16, v240
	v_add_u32_e32 v1, 4, v16
	v_cmp_lt_i32_e32 vcc, -1, v16
	v_add_u32_e32 v10, 8, v16
	v_min_u32_e32 v13, v1, v240
	v_cndmask_b32_e32 v0, 0, v0, vcc
	v_cmp_lt_i32_e32 vcc, -1, v1
	v_add_u32_e32 v11, 12, v16
	v_min_u32_e32 v14, v10, v240
	v_cndmask_b32_e32 v1, 0, v13, vcc
	v_cmp_lt_i32_e32 vcc, -1, v10
	v_add_u32_e32 v12, 16, v16
	v_min_u32_e32 v15, v11, v240
	v_cndmask_b32_e32 v10, 0, v14, vcc
	v_cmp_lt_i32_e32 vcc, -1, v11
	v_min_u32_e32 v17, v12, v240
	v_mul_lo_u32 v0, v0, s92
	v_cndmask_b32_e32 v11, 0, v15, vcc
	v_cmp_lt_i32_e32 vcc, -1, v12
	v_add_u32_e32 v96, s91, v0
	v_mul_lo_u32 v14, v1, s92
	v_cndmask_b32_e32 v12, 0, v17, vcc
	v_lshlrev_b32_e32 v241, 1, v210
	v_mul_lo_u32 v17, v10, s92
	v_mul_lo_u32 v18, v11, s92
	v_mul_lo_u32 v19, v12, s92
	v_lshlrev_b64 v[0:1], 6, v[216:217]
	v_lshlrev_b64 v[10:11], 11, v[216:217]
	v_lshlrev_b64 v[12:13], 11, v[96:97]
	v_add_u32_e32 v96, s91, v14
	v_lshl_add_u64 v[0:1], s[28:29], 0, v[0:1]
	v_lshl_add_u64 v[10:11], v[208:209], 0, v[10:11]
	v_or_b32_e32 v12, v12, v241
	v_lshlrev_b64 v[14:15], 11, v[96:97]
	v_add_u32_e32 v96, s91, v17
	flat_load_dword v17, v[0:1]
	flat_load_dwordx4 v[98:101], v[10:11]
	flat_load_dwordx4 v[102:105], v[10:11] offset:32
	flat_load_dwordx4 v[106:109], v[10:11] offset:64
	flat_load_dwordx4 v[110:113], v[10:11] offset:96
	flat_load_dwordx4 v[114:117], v[10:11] offset:128
	flat_load_dwordx4 v[118:121], v[10:11] offset:160
	flat_load_dwordx4 v[122:125], v[10:11] offset:192
	flat_load_dwordx4 v[126:129], v[10:11] offset:224
	s_waitcnt lgkmcnt(0)
	v_lshl_add_u64 v[0:1], s[70:71], 0, v[12:13]
	v_lshl_add_u64 v[10:11], s[78:79], 0, v[12:13]
	v_or_b32_e32 v14, v14, v241
	v_lshlrev_b64 v[12:13], 11, v[96:97]
	v_add_u32_e32 v96, s91, v18
	flat_load_dwordx4 v[130:133], v[0:1]
	flat_load_dwordx4 v[134:137], v[10:11]
	v_lshl_add_u64 v[0:1], s[70:71], 0, v[14:15]
	v_lshl_add_u64 v[10:11], s[78:79], 0, v[14:15]
	v_or_b32_e32 v12, v12, v241
	v_lshlrev_b64 v[14:15], 11, v[96:97]
	v_add_u32_e32 v96, s91, v19
	flat_load_dwordx4 v[138:141], v[0:1]
	flat_load_dwordx4 v[142:145], v[10:11]
	v_lshl_add_u64 v[0:1], s[70:71], 0, v[12:13]
	v_lshl_add_u64 v[10:11], s[78:79], 0, v[12:13]
	v_or_b32_e32 v14, v14, v241
	v_lshlrev_b64 v[12:13], 11, v[96:97]
	flat_load_dwordx4 v[146:149], v[0:1]
	flat_load_dwordx4 v[150:153], v[10:11]
	v_lshl_add_u64 v[0:1], s[70:71], 0, v[14:15]
	v_or_b32_e32 v12, v12, v241
	v_lshl_add_u64 v[10:11], s[78:79], 0, v[14:15]
	flat_load_dwordx4 v[154:157], v[0:1]
	flat_load_dwordx4 v[158:161], v[10:11]
	v_lshl_add_u64 v[0:1], s[70:71], 0, v[12:13]
	v_lshl_add_u64 v[10:11], s[78:79], 0, v[12:13]
	flat_load_dwordx4 v[162:165], v[0:1]
	flat_load_dwordx4 v[166:169], v[10:11]
	v_add_u32_e32 v0, 20, v16
	v_min_u32_e32 v1, v0, v240
	v_cmp_lt_i32_e32 vcc, -1, v0
	v_mov_b32_e32 v245, 0
	s_xor_b64 s[84:85], s[60:61], -1
	v_cndmask_b32_e32 v0, 0, v1, vcc
	v_mul_lo_u32 v0, v0, s92
	v_add_u32_e32 v96, s91, v0
	v_lshlrev_b64 v[0:1], 11, v[96:97]
	v_or_b32_e32 v0, v0, v241
	s_mov_b32 s40, 0
	v_add_u32_e32 v243, s94, v203
	v_mov_b32_e32 v246, 0xf149f2ca
	v_mov_b32_e32 v244, v234
	v_mov_b32_e32 v48, 0
	v_mov_b32_e32 v49, v245
	s_waitcnt vmcnt(18)
	v_add_f32_e32 v2, v2, v3
	v_add_f32_e32 v3, v4, v5
	v_add_f32_e32 v4, v6, v7
	v_add_f32_e32 v5, v8, v9
	v_add_f32_e32 v2, v2, v3
	v_add_f32_e32 v3, v4, v5
	v_add_f32_e32 v2, v2, v3
	v_fmamk_f32 v2, v2, 0x3a000000, v220
	v_rsq_f32_e32 v4, v2
	v_lshl_add_u64 v[2:3], s[70:71], 0, v[0:1]
	v_lshl_add_u64 v[0:1], s[78:79], 0, v[0:1]
	flat_load_dwordx4 v[170:173], v[2:3]
	flat_load_dwordx4 v[174:177], v[0:1]
	v_add_u32_e32 v0, 24, v16
	v_min_u32_e32 v1, v0, v240
	v_cmp_lt_i32_e32 vcc, -1, v0
	v_mov_b32_e32 v50, v245
	v_mov_b32_e32 v51, v245
	v_cndmask_b32_e32 v0, 0, v1, vcc
	v_mul_lo_u32 v0, v0, s92
	v_add_u32_e32 v96, s91, v0
	v_lshlrev_b64 v[0:1], 11, v[96:97]
	v_or_b32_e32 v0, v0, v241
	v_lshl_add_u64 v[2:3], s[70:71], 0, v[0:1]
	v_lshl_add_u64 v[0:1], s[78:79], 0, v[0:1]
	flat_load_dwordx4 v[178:181], v[2:3]
	flat_load_dwordx4 v[182:185], v[0:1]
	v_add_u32_e32 v0, 28, v16
	v_min_u32_e32 v1, v0, v240
	v_cmp_lt_i32_e32 vcc, -1, v0
	v_mov_b32_e32 v52, v245
	v_mov_b32_e32 v53, v245
	v_cndmask_b32_e32 v0, 0, v1, vcc
	v_mul_lo_u32 v0, v0, s92
	v_add_u32_e32 v96, s91, v0
	v_lshlrev_b64 v[0:1], 11, v[96:97]
	v_or_b32_e32 v0, v0, v241
	v_lshl_add_u64 v[2:3], s[70:71], 0, v[0:1]
	v_lshl_add_u64 v[0:1], s[78:79], 0, v[0:1]
	flat_load_dwordx4 v[186:189], v[2:3]
	flat_load_dwordx4 v[190:193], v[0:1]
	v_mul_f32_e32 v0, v4, v4
	v_mul_f32_e32 v0, v17, v0
	v_fmamk_f32 v0, v0, 0x3c000000, v220
	v_rsq_f32_e32 v0, v0
	v_add_u32_e32 v96, s94, v228
	v_mov_b32_e32 v54, v245
	v_mov_b32_e32 v55, v245
	v_mul_f32_e32 v0, v4, v0
	v_mul_f32_e32 v242, 0x3e0293ee, v0
	v_mov_b32_e32 v56, v245
	v_mov_b32_e32 v57, v245
	v_mov_b32_e32 v58, v245
	v_mov_b32_e32 v59, v245
	v_mov_b32_e32 v60, v245
	v_mov_b32_e32 v61, v245
	v_mov_b32_e32 v62, v245
	v_mov_b32_e32 v63, v245
	v_mov_b32_e32 v32, 0
	v_mov_b32_e32 v33, v245
	v_mov_b32_e32 v34, v245
	v_mov_b32_e32 v35, v245
	v_mov_b32_e32 v36, v245
	v_mov_b32_e32 v37, v245
	v_mov_b32_e32 v38, v245
	v_mov_b32_e32 v39, v245
	v_mov_b32_e32 v40, v245
	v_mov_b32_e32 v41, v245
	v_mov_b32_e32 v42, v245
	v_mov_b32_e32 v43, v245
	v_mov_b32_e32 v44, v245
	v_mov_b32_e32 v45, v245
	v_mov_b32_e32 v46, v245
	v_mov_b32_e32 v47, v245
	v_mov_b32_e32 v16, 0
	v_mov_b32_e32 v17, v245
	v_mov_b32_e32 v18, v245
	v_mov_b32_e32 v19, v245
	v_mov_b32_e32 v20, v245
	v_mov_b32_e32 v21, v245
	v_mov_b32_e32 v22, v245
	v_mov_b32_e32 v23, v245
	v_mov_b32_e32 v24, v245
	v_mov_b32_e32 v25, v245
	v_mov_b32_e32 v26, v245
	v_mov_b32_e32 v27, v245
	v_mov_b32_e32 v28, v245
	v_mov_b32_e32 v29, v245
	v_mov_b32_e32 v30, v245
	v_mov_b32_e32 v31, v245
	v_mov_b32_e32 v0, 0
	v_mov_b32_e32 v1, v245
	v_mov_b32_e32 v2, v245
	v_mov_b32_e32 v3, v245
	v_mov_b32_e32 v4, v245
	v_mov_b32_e32 v5, v245
	v_mov_b32_e32 v6, v245
	v_mov_b32_e32 v7, v245
	v_mov_b32_e32 v8, v245
	v_mov_b32_e32 v9, v245
	v_mov_b32_e32 v10, v245
	v_mov_b32_e32 v11, v245
	v_mov_b32_e32 v12, v245
	v_mov_b32_e32 v13, v245
	v_mov_b32_e32 v14, v245
	v_mov_b32_e32 v15, v245
